# norm2 rows loaded one iteration ahead; the barrier after the prologue is the XCD barrier instead of the cooperative-groups sync
# speedup vs baseline: 1.0706x; 1.0118x over previous
; #define LAS __attribute__((address_space(3)))
; __global__ void __launch_bounds__(NTHREADS, 2) fwd_kernel(Params P_) {
;     cg::grid_group grid = cg::this_grid();
;     extern __shared__ __attribute__((aligned(16))) unsigned char lds_k[];
;     volatile LAS unsigned* bst = (volatile LAS unsigned*)((LAS unsigned char*)lds_k + LDS_BYTES - 64);
;     if (threadIdx.x < 2) bst[threadIdx.x] = 0u;
;     __syncthreads();
;     const XcdBarrier bar = xcd_barrier_post((unsigned*)(P_.ws + WS_BAR), bst);
_Z10fwd_kernel6Params:
	s_mov_b32 s101, 0
	s_load_dwordx4 s[12:15], s[0:1], 0xf0
	s_load_dwordx2 s[92:93], s[0:1], 0x100
	s_mov_b64 s[86:87], s[0:1]
	s_add_u32 s0, s86, 0x100
	v_and_b32_e32 v228, 0x3ff, v0
	s_mov_b32 s82, s2
	s_addc_u32 s1, s87, 0
	v_cmp_gt_u32_e32 vcc, 2, v228
	s_and_saveexec_b64 s[2:3], vcc
	v_lshl_add_u32 v1, v228, 2, 0
	v_add_u32_e32 v1, 0x23fc0, v1
	v_mov_b32_e32 v2, 0
	ds_write_b32 v1, v2
	s_or_b64 exec, exec, s[2:3]
	s_waitcnt lgkmcnt(0)
	s_barrier
	s_add_u32 s8, s12, 0x11256000
	s_getreg_b32 s2, hwreg(HW_REG_XCC_ID, 0, 4)
	s_addc_u32 s9, s13, 0
	s_and_b32 s33, s2, 15
	v_cmp_eq_u32_e64 s[4:5], 0, v228
	s_mov_b64 s[2:3], exec
	s_nop 0
	v_writelane_b32 v253, s4, 0
	s_nop 1
	v_writelane_b32 v253, s5, 1
	s_and_b64 s[4:5], s[2:3], s[4:5]
	s_mov_b64 exec, s[4:5]
	s_cbranch_execz .LBB0_5
	s_mov_b64 s[4:5], exec
	v_mbcnt_lo_u32_b32 v1, s4, 0
	v_mbcnt_hi_u32_b32 v1, s5, v1
	v_cmp_eq_u32_e32 vcc, 0, v1
	s_and_b64 s[6:7], exec, vcc
	s_mov_b64 exec, s[6:7]
	s_cbranch_execz .LBB0_5
	s_lshl_b32 s6, s33, 8
	s_bcnt1_i32_b64 s4, s[4:5]
	v_mov_b32_e32 v1, s6
	v_mov_b32_e32 v2, s4
	global_atomic_add v1, v2, s[8:9] offset:1024

; #define KARG const __attribute__((address_space(4))) Params* Pp = (const __attribute__((address_space(4))) Params*)__builtin_amdgcn_kernarg_segment_ptr(); asm volatile("" : "+s"(Pp)); PARAMS P = *Pp;
; __global__ void __launch_bounds__(NTHREADS, 2) fwd_kernel(Params P_) {
;     ...
;     const int hi = P_.hi < NPHASE ? P_.hi : NPHASE;
;     int ph0 = P_.lo;
;     if (ph0 == 0) {
;         { KARG if (PHMASK & 1) run_phase<0>(P, 0, 0); }
;         ph0 = 1;
;         if (ph0 < hi) grid.sync();
;     }
;     for (int ph = ph0; ph < hi; ++ph) {
;         KARG
;         int kind, l, g; phase_decode(ph, kind, l, g);
.LBB0_86:
	s_min_i32 s83, s15, 52
	s_cmp_lt_i32 s83, 2
	s_cbranch_scc1 .LBB0_1020
	s_mov_b32 s14, 0
	s_mov_b32 s101, 1
.LBB0_99:
	s_add_u32 s36, s12, 0x11256200
	s_load_dword s1, s[86:87], 0x108
	s_addc_u32 s37, s13, 0
	s_add_u32 s78, s12, 0x11256400
	s_addc_u32 s79, s13, 0
	s_add_u32 s34, s12, 0x11256500
	s_mul_i32 s0, s93, s92
	s_addc_u32 s35, s13, 0
	s_waitcnt lgkmcnt(0)
	s_mul_i32 s90, s0, s1
	s_add_u32 s0, s12, 0x11256600
	s_addc_u32 s1, s13, 0
	v_writelane_b32 v253, s0, 2
	v_mov_b32_e32 v33, 0
	v_mbcnt_lo_u32_b32 v0, -1, 0
	v_writelane_b32 v253, s1, 3
	s_add_u32 s0, s12, 0x11256700
	s_addc_u32 s1, s13, 0
	v_writelane_b32 v253, s0, 4
	v_mov_b64_e32 v[196:197], 0x200
	v_mov_b64_e32 v[198:199], 0x1ff
	v_writelane_b32 v253, s1, 5
	s_add_u32 s0, s12, 0x11256800
	s_addc_u32 s1, s13, 0
	v_writelane_b32 v253, s0, 6
	v_mov_b32_e32 v229, 0x358637bd
	v_mov_b32_e32 v230, 0x3ecc95a3
	v_writelane_b32 v253, s1, 7
	s_add_u32 s0, s12, 0x11256900
	s_addc_u32 s1, s13, 0
	v_writelane_b32 v253, s0, 8
	v_mov_b32_e32 v231, 1
	v_mov_b64_e32 v[200:201], 0xb42
	v_writelane_b32 v253, s1, 9
	s_add_u32 s0, s12, 0x11256a00
	s_addc_u32 s1, s13, 0
	v_writelane_b32 v253, s0, 10
	v_mov_b64_e32 v[202:203], 0xb41
	v_mov_b32_e32 v232, 0x42800000
	v_writelane_b32 v253, s1, 11
	s_add_u32 s0, s12, 0x11256b00
	s_addc_u32 s1, s13, 0
	v_writelane_b32 v253, s0, 12
	v_mov_b32_e32 v233, 0x42000000
	v_not_b32_e32 v234, 63
	v_writelane_b32 v253, s1, 13
	s_add_u32 s0, s12, 0x11256c00
	s_addc_u32 s1, s13, 0
	v_writelane_b32 v253, s0, 14
	v_mbcnt_hi_u32_b32 v235, -1, v0
	v_bfrev_b32_e32 v236, 0.5
	v_writelane_b32 v253, s1, 15
	s_add_u32 s0, s12, 0x11256d00
	s_addc_u32 s1, s13, 0
	v_writelane_b32 v253, s0, 16
	v_mov_b32_e32 v237, 0x7f800000
	v_mov_b32_e32 v238, 0x7fc00000
	v_writelane_b32 v253, s1, 17
	s_add_u32 s0, s12, 0x11256e00
	s_addc_u32 s1, s13, 0
	v_writelane_b32 v253, s0, 18
	v_mov_b32_e32 v239, 0xff800000
	v_mov_b32_e32 v240, 0x41b17218
	v_writelane_b32 v253, s1, 19
	s_add_u32 s0, s12, 0x11256f00
	s_addc_u32 s1, s13, 0
	v_writelane_b32 v253, s0, 20
	v_mov_b32_e32 v241, 0x1800
	s_mov_b32 s15, 0xbfb8aa3b
	v_writelane_b32 v253, s1, 21
	s_add_u32 s0, s12, 0x11257000
	s_addc_u32 s1, s13, 0
	v_writelane_b32 v253, s0, 22
	s_movk_i32 s91, 0x1600
	s_mov_b32 s81, 0x800000
	v_writelane_b32 v253, s1, 23
	s_add_u32 s0, s12, 0x11257100
	s_addc_u32 s1, s13, 0
	v_writelane_b32 v253, s0, 24
	s_mov_b32 s22, 0xc2fc0000
	s_movk_i32 s23, 0x1fff
	v_writelane_b32 v253, s1, 25
	s_add_u32 s0, s12, 0x11257200
	s_addc_u32 s1, s13, 0
	v_writelane_b32 v253, s0, 26
	s_movk_i32 s93, 0x21ff
	s_movk_i32 s64, 0x2210
	v_writelane_b32 v253, s1, 27
	s_add_u32 s0, s12, 0x11257300
	s_addc_u32 s1, s13, 0
	v_writelane_b32 v253, s0, 28
	s_cmp_eq_u32 s33, 15
	s_movk_i32 s24, 0x220f
	v_writelane_b32 v253, s1, 29
	s_cselect_b64 s[0:1], -1, 0
	v_writelane_b32 v253, s0, 30
	s_cmp_eq_u32 s33, 14
	s_movk_i32 s25, 0x1800
	v_writelane_b32 v253, s1, 31
	s_cselect_b64 s[0:1], -1, 0
	v_writelane_b32 v253, s0, 32
	s_cmp_eq_u32 s33, 13
	s_mov_b32 s26, 0x5040100
	v_writelane_b32 v253, s1, 33
	s_cselect_b64 s[0:1], -1, 0
	v_writelane_b32 v253, s0, 34
	s_cmp_eq_u32 s33, 12
	s_movk_i32 s28, 0xffb0
	v_writelane_b32 v253, s1, 35
	s_cselect_b64 s[0:1], -1, 0
	v_writelane_b32 v253, s0, 36
	s_cmp_eq_u32 s33, 11
	s_mov_b32 s29, 0x7f800000
	v_writelane_b32 v253, s1, 37
	s_cselect_b64 s[0:1], -1, 0
	v_writelane_b32 v253, s0, 38
	s_cmp_eq_u32 s33, 10
	s_mov_b32 s30, 0x3f317217
	v_writelane_b32 v253, s1, 39
	s_cselect_b64 s[0:1], -1, 0
	v_writelane_b32 v253, s0, 40
	s_cmp_eq_u32 s33, 9
	s_mov_b64 s[76:77], 0x80
	v_writelane_b32 v253, s1, 41
	s_cselect_b64 s[0:1], -1, 0
	v_writelane_b32 v253, s0, 42
	s_cmp_eq_u32 s33, 8
	s_mov_b32 s80, 0x3e000000
	v_writelane_b32 v253, s1, 43
	s_cselect_b64 s[0:1], -1, 0
	v_writelane_b32 v253, s0, 44
	s_cmp_eq_u32 s33, 7
	s_mov_b64 s[84:85], 0x1000
	v_writelane_b32 v253, s1, 45
	s_cselect_b64 s[0:1], -1, 0
	v_writelane_b32 v253, s0, 46
	s_cmp_eq_u32 s33, 6
	s_mov_b64 s[88:89], 0x2000
	v_writelane_b32 v253, s1, 47
	s_cselect_b64 s[0:1], -1, 0
	v_writelane_b32 v253, s0, 48
	s_cmp_eq_u32 s33, 5
	s_nop 0
	v_writelane_b32 v253, s1, 49
	s_cselect_b64 s[0:1], -1, 0
	v_writelane_b32 v253, s0, 50
	s_cmp_eq_u32 s33, 4
	s_nop 0
	v_writelane_b32 v253, s1, 51
	s_cselect_b64 s[0:1], -1, 0
	v_writelane_b32 v253, s0, 52
	s_cmp_eq_u32 s33, 3
	s_nop 0
	v_writelane_b32 v253, s1, 53
	s_cselect_b64 s[0:1], -1, 0
	v_writelane_b32 v253, s0, 54
	s_cmp_eq_u32 s33, 2
	s_nop 0
	v_writelane_b32 v253, s1, 55
	s_cselect_b64 s[0:1], -1, 0
	v_writelane_b32 v253, s0, 56
	s_cmp_eq_u32 s33, 1
	s_nop 0
	v_writelane_b32 v253, s1, 57
	s_cselect_b64 s[0:1], -1, 0
	v_writelane_b32 v253, s0, 58
	s_cmp_eq_u32 s33, 0
	s_nop 0
	v_writelane_b32 v253, s1, 59
	s_cselect_b64 s[0:1], -1, 0
	v_writelane_b32 v253, s0, 60
	s_nop 1
	v_writelane_b32 v253, s1, 61
	s_lshl_b32 s0, s33, 8
	s_add_u32 s0, s8, s0
	s_addc_u32 s1, s9, 0
	s_add_u32 s2, s0, 0x1400
	s_addc_u32 s3, s1, 0
	s_add_u32 s0, s0, 0x2400
	s_addc_u32 s1, s1, 0
	v_writelane_b32 v254, s0, 0
	v_writelane_b32 v253, s2, 62
	s_nop 0
	v_writelane_b32 v254, s1, 1
	s_add_u32 s0, s12, 0x11259400
	s_addc_u32 s1, s13, 0
	v_writelane_b32 v254, s0, 2
	v_writelane_b32 v253, s3, 63
	s_nop 0
	v_writelane_b32 v254, s1, 3
	s_add_u32 s0, s12, 0x11259500
	s_addc_u32 s1, s13, 0
	v_writelane_b32 v254, s0, 4
	s_add_i32 s27, 0, 0x10400
	s_mov_b32 s13, 0
	v_writelane_b32 v254, s1, 5
	s_add_i32 s0, 0, 0x22000
	v_writelane_b32 v254, s0, 6
	s_add_i32 s0, 0, 0x22400
	v_writelane_b32 v254, s0, 7
	s_add_i32 s0, 0, 0x21800
	v_writelane_b32 v254, s0, 8
	s_add_i32 s0, 0, 0x21c00
	v_writelane_b32 v254, s0, 9
	s_add_i32 s0, 0, 0x207e0
	v_writelane_b32 v254, s0, 10
	s_add_i32 s0, 0, 0x23fc0
	v_writelane_b32 v254, s0, 11
	s_add_i32 s0, 0, 0x23fc4
	v_writelane_b32 v254, s0, 12
	v_writelane_b32 v254, s82, 13
	v_writelane_b32 v254, s86, 14
	s_nop 1
	v_writelane_b32 v254, s87, 15
	v_writelane_b32 v254, s83, 16
	v_writelane_b32 v254, s90, 17
	v_writelane_b32 v254, s36, 18
	s_nop 1
	v_writelane_b32 v254, s37, 19
	v_writelane_b32 v254, s78, 20
	s_nop 1
	v_writelane_b32 v254, s79, 21
	v_writelane_b32 v254, s34, 22
	s_nop 1
	v_writelane_b32 v254, s35, 23
	s_cmp_eq_u32 s101, 1
	s_cbranch_scc1 .LBB0_964
	s_branch .LBB0_103

; __device__ __forceinline__ unsigned cvt_pk_bf16(float lo, float hi) { const f32x2_cv v = {lo, hi}; const bf16x2_cv b = __builtin_convertvector(v, bf16x2_cv); return __builtin_bit_cast(unsigned, b); }
; template <int RB> DI void norm_rows(float* X, const f32x4 (&gv)[4], bf16_t* XN, const float* wsm, float* SM, int row0, int lane, const float* part) {
;     ...
;         const int row = row0 + r; const f32x4* xr = (const f32x4*)(X + (size_t)row * D); float ss = 0.f;
; #pragma unroll
;         for (int j = 0; j < 4; ++j) v[r][j] = xr[lane + 64 * j];
;         if (part && row >= MMAIN) {
; #pragma unroll 1
;             for (int kh = 0; kh < NKSL; ++kh) { const f32x4* pr = (const f32x4*)(part + ((size_t)kh * (MTOT - MMAIN) + (row - MMAIN)) * 1024);
; #pragma unroll
;                 for (int j = 0; j < 4; ++j) v[r][j] += pr[lane + 64 * j]; }
; #pragma unroll
;             for (int j = 0; j < 4; ++j) ((f32x4*)(X + (size_t)row * D))[lane + 64 * j] = v[r][j];
;         }
; #pragma unroll
;         for (int j = 0; j < 4; ++j) ss += (v[r][j][0] * v[r][j][0] + v[r][j][1] * v[r][j][1]) + (v[r][j][2] * v[r][j][2] + v[r][j][3] * v[r][j][3]);
;         const float rs = rsqrtf(wave_sum(ss) * (1.f / D) + EPS);
;         u32x2* o = (u32x2*)(XN + (size_t)row * D);
; #pragma unroll
;         for (int j = 0; j < 4; ++j) { v[r][j] = v[r][j] * rs * gv[j]; u32x2 w; w.x = cvt_pk_bf16(v[r][j][0], v[r][j][1]); w.y = cvt_pk_bf16(v[r][j][2], v[r][j][3]); o[lane + 64 * j] = w; }
; DI void norm_phase(float* X, const float* gain, bf16_t* XN, const float* wsm, float* SM, int wave, int lane, const float* part = nullptr) {
;     ...
;     else { for (int row = gw; row < MTOT; row += NGW) norm_rows<1>(X, gv, XN, nullptr, nullptr, row, lane, part); }
.LBB0_196:
	s_and_b64 vcc, exec, s[4:5]
	s_cbranch_vccz .LBB0_200
	s_waitcnt vmcnt(0)
	v_mov_b32_e32 v0, v228
	v_mov_b32_e32 v1, v228
	s_nop 0
	v_readfirstlane_b32 s0, v1
	s_ashr_i32 s1, s0, 6
	s_mov_b32 s0, s82
	s_lshl_b32 s2, s0, 3
	s_add_i32 s4, s2, s1
	s_mov_b32 s0, s92
	s_cmp_gt_i32 s4, 0x82ff
	s_cbranch_scc1 .LBB0_200
	s_load_dwordx2 s[2:3], s[18:19], 0xc8
	s_load_dwordx2 s[6:7], s[18:19], 0xf0
	s_lshl_b32 s10, s96, 10
	s_ashr_i32 s11, s10, 31
	s_lshl_b64 s[10:11], s[10:11], 2
	v_and_b32_e32 v16, 63, v0
	s_waitcnt lgkmcnt(0)
	s_add_u32 s2, s2, s10
	s_addc_u32 s3, s3, s11
	v_lshlrev_b32_e32 v17, 4, v16
	global_load_dwordx4 v[0:3], v17, s[2:3]
	global_load_dwordx4 v[4:7], v17, s[2:3] offset:1024
	global_load_dwordx4 v[8:11], v17, s[2:3] offset:2048
	global_load_dwordx4 v[12:15], v17, s[2:3] offset:3072
	s_ashr_i32 s5, s4, 31
	s_lshl_b32 s16, s0, 3
	s_lshl_b64 s[0:1], s[4:5], 11
	v_lshl_or_b32 v28, v16, 3, s0
	v_mov_b32_e32 v29, s1
	s_ashr_i32 s17, s16, 31
	s_lshl_b64 s[0:1], s[4:5], 12
	s_lshl_b64 s[38:39], s[16:17], 11
	v_or_b32_e32 v30, s0, v17
	v_mov_b32_e32 v31, s1
	s_lshl_b64 s[40:41], s[16:17], 12
	v_lshl_add_u64 v[128:129], s[6:7], 0, v[30:31]
	global_load_dwordx4 v[112:115], v[128:129], off
	global_load_dwordx4 v[116:119], v[128:129], off offset:1024
	global_load_dwordx4 v[120:123], v[128:129], off offset:2048
	global_load_dwordx4 v[124:127], v[128:129], off offset:3072
	v_lshl_add_u64 v[30:31], v[30:31], 0, s[40:41]
	s_waitcnt vmcnt(0)
	s_branch .Ln2_in
.LBB0_199:
	s_waitcnt vmcnt(4)
.Ln2_in:
	v_mov_b64_e32 v[34:35], v[112:113]
	v_mov_b64_e32 v[36:37], v[114:115]
	v_mov_b64_e32 v[24:25], v[116:117]
	v_mov_b64_e32 v[26:27], v[118:119]
	v_mov_b64_e32 v[20:21], v[120:121]
	v_mov_b64_e32 v[22:23], v[122:123]
	v_mov_b64_e32 v[16:17], v[124:125]
	v_mov_b64_e32 v[18:19], v[126:127]
	v_lshl_add_u64 v[128:129], s[6:7], 0, v[30:31]
	global_load_dwordx4 v[112:115], v[128:129], off
	global_load_dwordx4 v[116:119], v[128:129], off offset:1024
	global_load_dwordx4 v[120:123], v[128:129], off offset:2048
	global_load_dwordx4 v[124:127], v[128:129], off offset:3072
	v_lshl_add_u64 v[30:31], v[30:31], 0, s[40:41]
	s_add_i32 s4, s4, s16
	s_cmp_gt_i32 s4, 0x82ff
	v_pk_mul_f32 v[38:39], v[36:37], v[36:37]
	v_pk_mul_f32 v[40:41], v[34:35], v[34:35]
	v_mul_f32_e32 v32, v20, v20
	v_pk_mov_b32 v[42:43], v[40:41], v[38:39] op_sel:[1,0]
	v_mov_b32_e32 v41, v39
	v_pk_add_f32 v[38:39], v[42:43], v[40:41]
	v_pk_mul_f32 v[40:41], v[26:27], v[26:27]
	v_pk_mul_f32 v[42:43], v[24:25], v[24:25]
	v_pk_add_f32 v[38:39], v[38:39], v[38:39] op_sel_hi:[0,1]
	v_pk_mov_b32 v[44:45], v[42:43], v[40:41] op_sel:[1,0]
	v_mov_b32_e32 v43, v41
	v_pk_add_f32 v[40:41], v[44:45], v[42:43]
	v_pk_fma_f32 v[42:43], v[20:21], v[20:21], v[32:33] op_sel_hi:[1,1,0]
	v_mul_f32_e32 v32, v22, v22
	v_pk_add_f32 v[40:41], v[40:41], v[40:41] op_sel_hi:[0,1]
	v_pk_fma_f32 v[44:45], v[22:23], v[22:23], v[32:33] op_sel_hi:[1,1,0]
	v_mul_f32_e32 v42, v16, v16
	v_mul_f32_e32 v44, v17, v17
	v_mul_f32_e32 v38, v18, v18
	v_mul_f32_e32 v40, v19, v19
	v_pk_add_f32 v[42:43], v[42:43], v[44:45]
	v_pk_add_f32 v[38:39], v[38:39], v[40:41]
	s_nop 0
	v_pk_add_f32 v[38:39], v[42:43], v[38:39]
	s_nop 0
	v_add_f32_e32 v32, v38, v39
	s_nop 1
	v_add_f32_dpp v32, v32, v32 quad_perm:[1,0,3,2] row_mask:0xf bank_mask:0xf bound_ctrl:1
	s_nop 1
	v_add_f32_dpp v32, v32, v32 quad_perm:[2,3,0,1] row_mask:0xf bank_mask:0xf bound_ctrl:1
	s_nop 1
	v_add_f32_dpp v32, v32, v32 row_half_mirror row_mask:0xf bank_mask:0xf bound_ctrl:1
	s_nop 1
	v_add_f32_dpp v32, v32, v32 row_mirror row_mask:0xf bank_mask:0xf bound_ctrl:1
	s_nop 0
	v_readlane_b32 s2, v32, 16
	v_readlane_b32 s3, v32, 48
	v_readlane_b32 s0, v32, 0
	v_readlane_b32 s1, v32, 32
	v_mov_b32_e32 v38, s2
	v_mov_b32_e32 v39, s3
	v_pk_add_f32 v[38:39], s[0:1], v[38:39]
	s_mov_b32 s0, 0x8300000
	v_add_f32_e32 v32, v38, v39
	v_fmamk_f32 v32, v32, 0x3a800000, v229
	v_cmp_gt_f32_e32 vcc, s81, v32
	v_mul_f32_e32 v38, 0x4b800000, v32
	s_nop 0
	v_cndmask_b32_e32 v32, v32, v38, vcc
	v_rsq_f32_e32 v32, v32
	s_nop 0
	v_mul_f32_e32 v38, 0x45800000, v32
	v_cndmask_b32_e32 v32, v32, v38, vcc
	v_pk_mul_f32 v[34:35], v[34:35], v[32:33] op_sel_hi:[1,0]
	v_pk_mul_f32 v[36:37], v[36:37], v[32:33] op_sel_hi:[1,0]
	v_pk_mul_f32 v[34:35], v[0:1], v[34:35]
	v_pk_mul_f32 v[36:37], v[2:3], v[36:37]
	v_cvt_pk_bf16_f32 v34, v34, v35
	v_cvt_pk_bf16_f32 v35, v36, v37
	v_lshl_add_u64 v[36:37], s[6:7], 0, v[28:29]
	v_pk_mul_f32 v[24:25], v[24:25], v[32:33] op_sel_hi:[1,0]
	v_pk_mul_f32 v[26:27], v[26:27], v[32:33] op_sel_hi:[1,0]
	v_pk_mul_f32 v[20:21], v[20:21], v[32:33] op_sel_hi:[1,0]
	v_pk_mul_f32 v[22:23], v[22:23], v[32:33] op_sel_hi:[1,0]
	v_pk_mul_f32 v[16:17], v[16:17], v[32:33] op_sel_hi:[1,0]
	v_pk_mul_f32 v[18:19], v[18:19], v[32:33] op_sel_hi:[1,0]
	v_add_co_u32_e32 v36, vcc, s0, v36
	v_pk_mul_f32 v[26:27], v[6:7], v[26:27]
	v_pk_mul_f32 v[24:25], v[4:5], v[24:25]
	v_pk_mul_f32 v[22:23], v[10:11], v[22:23]
	v_pk_mul_f32 v[20:21], v[8:9], v[20:21]
	v_pk_mul_f32 v[18:19], v[14:15], v[18:19]
	v_pk_mul_f32 v[16:17], v[12:13], v[16:17]
	v_addc_co_u32_e32 v37, vcc, 0, v37, vcc
	v_cvt_pk_bf16_f32 v24, v24, v25
	v_cvt_pk_bf16_f32 v25, v26, v27
	v_cvt_pk_bf16_f32 v20, v20, v21
	v_cvt_pk_bf16_f32 v21, v22, v23
	v_cvt_pk_bf16_f32 v16, v16, v17
	v_cvt_pk_bf16_f32 v17, v18, v19
	v_lshl_add_u64 v[28:29], v[28:29], 0, s[38:39]
	global_store_dwordx2 v[36:37], v[34:35], off
	global_store_dwordx2 v[36:37], v[24:25], off offset:512
	global_store_dwordx2 v[36:37], v[20:21], off offset:1024
	global_store_dwordx2 v[36:37], v[16:17], off offset:1536
	s_cbranch_scc0 .LBB0_199

; __global__ void __launch_bounds__(NTHREADS, 2) fwd_kernel(Params P_) {
	.amdhsa_kernel _Z10fwd_kernel6Params
		.amdhsa_group_segment_fixed_size 0
		.amdhsa_private_segment_fixed_size 0
		.amdhsa_kernarg_size 512
		.amdhsa_user_sgpr_count 2
		.amdhsa_user_sgpr_dispatch_ptr 0
		.amdhsa_user_sgpr_queue_ptr 0
		.amdhsa_user_sgpr_kernarg_segment_ptr 1
		.amdhsa_user_sgpr_dispatch_id 0
		.amdhsa_user_sgpr_kernarg_preload_length 0
		.amdhsa_user_sgpr_kernarg_preload_offset 0
		.amdhsa_user_sgpr_private_segment_size 0
		.amdhsa_uses_dynamic_stack 0
		.amdhsa_enable_private_segment 0
		.amdhsa_system_sgpr_workgroup_id_x 1
		.amdhsa_system_sgpr_workgroup_id_y 0
		.amdhsa_system_sgpr_workgroup_id_z 0
		.amdhsa_system_sgpr_workgroup_info 0
		.amdhsa_system_vgpr_workitem_id 2
		.amdhsa_next_free_vgpr 255
		.amdhsa_next_free_sgpr 102
		.amdhsa_accum_offset 256
		.amdhsa_reserve_vcc 1
		.amdhsa_float_round_mode_32 0
		.amdhsa_float_round_mode_16_64 0
		.amdhsa_float_denorm_mode_32 3
		.amdhsa_float_denorm_mode_16_64 3
		.amdhsa_dx10_clamp 1
		.amdhsa_ieee_mode 1
		.amdhsa_fp16_overflow 0
		.amdhsa_tg_split 0
		.amdhsa_exception_fp_ieee_invalid_op 0
		.amdhsa_exception_fp_denorm_src 0
		.amdhsa_exception_fp_ieee_div_zero 0
		.amdhsa_exception_fp_ieee_overflow 0
		.amdhsa_exception_fp_ieee_underflow 0
		.amdhsa_exception_fp_ieee_inexact 0
		.amdhsa_exception_int_div_zero 0
	.end_amdhsa_kernel

; __global__ void __launch_bounds__(NTHREADS, 2) fwd_kernel(Params P_) {
amdhsa.kernels:
  - .agpr_count:     0
    .args:
      - .offset:         0
        .size:           256
        .value_kind:     by_value
      - .offset:         256
        .size:           4
        .value_kind:     hidden_block_count_x
      - .offset:         260
        .size:           4
        .value_kind:     hidden_block_count_y
      - .offset:         264
        .size:           4
        .value_kind:     hidden_block_count_z
      - .offset:         268
        .size:           2
        .value_kind:     hidden_group_size_x
      - .offset:         270
        .size:           2
        .value_kind:     hidden_group_size_y
      - .offset:         272
        .size:           2
        .value_kind:     hidden_group_size_z
      - .offset:         274
        .size:           2
        .value_kind:     hidden_remainder_x
      - .offset:         276
        .size:           2
        .value_kind:     hidden_remainder_y
      - .offset:         278
        .size:           2
        .value_kind:     hidden_remainder_z
      - .offset:         296
        .size:           8
        .value_kind:     hidden_global_offset_x
      - .offset:         304
        .size:           8
        .value_kind:     hidden_global_offset_y
      - .offset:         312
        .size:           8
        .value_kind:     hidden_global_offset_z
      - .offset:         320
        .size:           2
        .value_kind:     hidden_grid_dims
      - .offset:         344
        .size:           8
        .value_kind:     hidden_multigrid_sync_arg
      - .offset:         376
        .size:           4
        .value_kind:     hidden_dynamic_lds_size
    .group_segment_fixed_size: 0
    .kernarg_segment_align: 8
    .kernarg_segment_size: 512
    .language:       OpenCL C
    .language_version:
      - 2
      - 0
    .max_flat_workgroup_size: 512
    .name:           _Z10fwd_kernel6Params
    .private_segment_fixed_size: 0
    .sgpr_count:     108
    .sgpr_spill_count: 172
    .symbol:         _Z10fwd_kernel6Params.kd
    .uniform_work_group_size: 1
    .uses_dynamic_stack: false
    .vgpr_count:     255
    .vgpr_spill_count: 0
    .wavefront_size: 64
